# v37 with dependency-flag poll back-off shortened (s_sleep 2 to s_sleep 1)
# speedup vs baseline: 1.0022x; 1.0022x over previous
; DI void wait_count(unsigned* ctr, unsigned target) {
;   if (threadIdx.x == 0) {
;     unsigned sp = 0;
;     while (__hip_atomic_load(ctr, __ATOMIC_RELAXED, __HIP_MEMORY_SCOPE_AGENT) < target) { __builtin_amdgcn_s_sleep(2); if (++sp > (1u << 24)) break; }
;     __builtin_amdgcn_fence(__ATOMIC_ACQUIRE, "agent");
;     asm volatile("s_waitcnt vmcnt(0)" ::: "memory");
;   }
;   __syncthreads();
; }
.LBB0_399:
	global_load_dword v1, v207, s[4:5] sc1
	s_mov_b64 s[6:7], -1
	s_waitcnt vmcnt(0)
	v_cmp_lt_u32_e32 vcc, 7, v1
	s_cbranch_vccnz .LBB0_398
	s_cmp_lg_u32 s8, 0
	s_sleep 1
	s_cbranch_scc0 .LBB0_397
	global_load_dword v1, v207, s[4:5] sc1
	s_waitcnt vmcnt(0)
	v_cmp_gt_u32_e32 vcc, 8, v1
	s_cbranch_vccz .LBB0_398
	s_sleep 1
	global_load_dword v1, v207, s[4:5] sc1
	s_waitcnt vmcnt(0)
	v_cmp_gt_u32_e32 vcc, 8, v1
	s_cbranch_vccz .LBB0_398
	s_sleep 1
	global_load_dword v1, v207, s[4:5] sc1
	s_waitcnt vmcnt(0)
	v_cmp_gt_u32_e32 vcc, 8, v1
	s_cbranch_vccz .LBB0_398
	s_sleep 1
	global_load_dword v1, v207, s[4:5] sc1
	s_waitcnt vmcnt(0)
	v_cmp_gt_u32_e32 vcc, 8, v1
	s_cbranch_vccz .LBB0_398
	s_sleep 1
	global_load_dword v1, v207, s[4:5] sc1
	s_waitcnt vmcnt(0)
	v_cmp_gt_u32_e32 vcc, 8, v1
	s_cbranch_vccz .LBB0_398
	s_sleep 1
	global_load_dword v1, v207, s[4:5] sc1
	s_waitcnt vmcnt(0)
	v_cmp_gt_u32_e32 vcc, 8, v1
	s_cbranch_vccz .LBB0_398
	s_sleep 1
	global_load_dword v1, v207, s[4:5] sc1
	s_waitcnt vmcnt(0)
	v_cmp_gt_u32_e32 vcc, 8, v1
	s_cbranch_vccz .LBB0_398
	s_sleep 1
	s_add_i32 s8, s8, -8
	s_mov_b64 s[6:7], 0
	s_branch .LBB0_398

; DI void wait_count(unsigned* ctr, unsigned target) {
;   if (threadIdx.x == 0) {
;     unsigned sp = 0;
;     while (__hip_atomic_load(ctr, __ATOMIC_RELAXED, __HIP_MEMORY_SCOPE_AGENT) < target) { __builtin_amdgcn_s_sleep(2); if (++sp > (1u << 24)) break; }
;     __builtin_amdgcn_fence(__ATOMIC_ACQUIRE, "agent");
;     asm volatile("s_waitcnt vmcnt(0)" ::: "memory");
;   }
;   __syncthreads();
; }
.LBB0_429:
	global_load_dword v1, v207, s[4:5] sc1
	s_mov_b64 s[6:7], -1
	s_waitcnt vmcnt(0)
	v_cmp_lt_u32_e32 vcc, 3, v1
	s_cbranch_vccnz .LBB0_428
	s_cmp_lg_u32 s3, 0
	s_sleep 1
	s_cbranch_scc0 .LBB0_427
	global_load_dword v1, v207, s[4:5] sc1
	s_waitcnt vmcnt(0)
	v_cmp_gt_u32_e32 vcc, 4, v1
	s_cbranch_vccz .LBB0_428
	s_sleep 1
	global_load_dword v1, v207, s[4:5] sc1
	s_waitcnt vmcnt(0)
	v_cmp_gt_u32_e32 vcc, 4, v1
	s_cbranch_vccz .LBB0_428
	s_sleep 1
	global_load_dword v1, v207, s[4:5] sc1
	s_waitcnt vmcnt(0)
	v_cmp_gt_u32_e32 vcc, 4, v1
	s_cbranch_vccz .LBB0_428
	s_sleep 1
	global_load_dword v1, v207, s[4:5] sc1
	s_waitcnt vmcnt(0)
	v_cmp_gt_u32_e32 vcc, 4, v1
	s_cbranch_vccz .LBB0_428
	s_sleep 1
	global_load_dword v1, v207, s[4:5] sc1
	s_waitcnt vmcnt(0)
	v_cmp_gt_u32_e32 vcc, 4, v1
	s_cbranch_vccz .LBB0_428
	s_sleep 1
	global_load_dword v1, v207, s[4:5] sc1
	s_waitcnt vmcnt(0)
	v_cmp_gt_u32_e32 vcc, 4, v1
	s_cbranch_vccz .LBB0_428
	s_sleep 1
	global_load_dword v1, v207, s[4:5] sc1
	s_waitcnt vmcnt(0)
	v_cmp_gt_u32_e32 vcc, 4, v1
	s_cbranch_vccz .LBB0_428
	s_add_i32 s3, s3, -8
	s_mov_b64 s[6:7], 0
	s_sleep 1
	s_branch .LBB0_428

; DI void wait_count(unsigned* ctr, unsigned target) {
;   if (threadIdx.x == 0) {
;     unsigned sp = 0;
;     while (__hip_atomic_load(ctr, __ATOMIC_RELAXED, __HIP_MEMORY_SCOPE_AGENT) < target) { __builtin_amdgcn_s_sleep(2); if (++sp > (1u << 24)) break; }
;     __builtin_amdgcn_fence(__ATOMIC_ACQUIRE, "agent");
;     asm volatile("s_waitcnt vmcnt(0)" ::: "memory");
;   }
;   __syncthreads();
; }
.LBB0_538:
	global_load_dword v18, v207, s[4:5] sc1
	s_mov_b64 s[6:7], -1
	s_waitcnt vmcnt(0)
	v_cmp_lt_u32_e32 vcc, 1, v18
	s_cbranch_vccnz .LBB0_537
	s_cmp_lg_u32 s13, 0
	s_sleep 1
	s_cbranch_scc0 .LBB0_536
	global_load_dword v18, v207, s[4:5] sc1
	s_waitcnt vmcnt(0)
	v_cmp_gt_u32_e32 vcc, 2, v18
	s_cbranch_vccz .LBB0_537
	s_sleep 1
	global_load_dword v18, v207, s[4:5] sc1
	s_waitcnt vmcnt(0)
	v_cmp_gt_u32_e32 vcc, 2, v18
	s_cbranch_vccz .LBB0_537
	s_sleep 1
	global_load_dword v18, v207, s[4:5] sc1
	s_waitcnt vmcnt(0)
	v_cmp_gt_u32_e32 vcc, 2, v18
	s_cbranch_vccz .LBB0_537
	s_sleep 1
	global_load_dword v18, v207, s[4:5] sc1
	s_waitcnt vmcnt(0)
	v_cmp_gt_u32_e32 vcc, 2, v18
	s_cbranch_vccz .LBB0_537
	s_sleep 1
	global_load_dword v18, v207, s[4:5] sc1
	s_waitcnt vmcnt(0)
	v_cmp_gt_u32_e32 vcc, 2, v18
	s_cbranch_vccz .LBB0_537
	s_sleep 1
	global_load_dword v18, v207, s[4:5] sc1
	s_waitcnt vmcnt(0)
	v_cmp_gt_u32_e32 vcc, 2, v18
	s_cbranch_vccz .LBB0_537
	s_sleep 1
	global_load_dword v18, v207, s[4:5] sc1
	s_waitcnt vmcnt(0)
	v_cmp_gt_u32_e32 vcc, 2, v18
	s_cbranch_vccz .LBB0_537
	s_sleep 1
	s_add_i32 s13, s13, -8
	s_mov_b64 s[6:7], 0
	s_branch .LBB0_537
